# P2/P12 GEMM loops: next K-tile's B0 fragments read in the shadow of the current tile's second MFMA block (12+12 LDS reads per super-phase instead of 16+8)
# baseline (speedup 1.0000x reference)
; __device__ __forceinline__ int fresh_tid() { int t = (int)threadIdx.x; asm volatile("" : "+v"(t)); return t; }
; #define PG8_STAGE(bufoff, gbase, voff) do { _Pragma("unroll") for (int _i = 0; _i < 2; ++_i) \
;         __builtin_amdgcn_global_load_lds((const unsigned*)((const char*)(gbase) + (voff)[_i]), (PG8_LAS unsigned*)(lds + (bufoff) + ldsw + _i * 8192), 16, 0, 0); } while (0)
; template <class Epi, class Sched, bool ALIGN_EPI = false, bool SP2 = false>
; __device__ __forceinline__ void gemm_phase(PG8_LAS unsigned char* lds, const Gemm g, const Sched& S, const Epi& E) {
;     const int tid = fresh_tid(), wid = __builtin_amdgcn_readfirstlane(tid >> 6), lane = tid & 63, wr = wid >> 2, wc = wid & 3, fr = lane & 15, fq = lane >> 4;
;     const int K = g.K, nt = K / BK;
;     unsigned voffA[2], voffB[2];
; #pragma unroll
;     for (int i = 0; i < 2; ++i) { int R, C; stage_rc(tid * 16 + i * 8192, R, C); const int Rb = Epi::PERM ? ((R & ~31) + perm32(R & 31)) : R;
;         voffA[i] = (unsigned)(R * K + C) * 2u; voffB[i] = (unsigned)(Rb * K + C) * 2u; }
;     const size_t kstep = (size_t)(BK * 2);
;     const size_t hstep = (size_t)HALF * K * 2;
;     const size_t tstep = 2 * hstep;
;     const unsigned ldsw = (unsigned)wid * 1024u;
;     const int aoff = lds_byte(wr * 64 + fr, fq * 8), boff = lds_byte(wc * 32 + fr, fq * 8);
;     ...
;     Unit cur, nxt; int ui = 0;
;     if (!S.next(0, cur)) return;
;     f32x4 acc[2][2][4][2];
; #pragma unroll
;     for (int a = 0; a < 2; ++a)
; #pragma unroll
;         for (int b = 0; b < 2; ++b)
; #pragma unroll
;             for (int m = 0; m < 4; ++m)
; #pragma unroll
;                 for (int n = 0; n < 2; ++n) acc[a][b][m][n] = (f32x4){0.f, 0.f, 0.f, 0.f};
;     bf16x8 At[4][2], B0[2][2], B1[2][2];
;     const char* cA = (const char*)g.A + (size_t)cur.pm * tstep; const char* cB = (const char*)g.Bt + (size_t)cur.pn * tstep;
;     S.a_ready(cur);
;     if constexpr (SP2) {
;         PG8_STAGE(PG8_SB(0, 0), cB, voffB); PG8_STAGE(PG8_SB(0, 1), cB + hstep, voffB); PG8_STAGE(PG8_SA(0, 0), cA, voffA); PG8_STAGE(PG8_SA(0, 1), cA + hstep, voffA);
;         if (wr == 1) PG8_BAR;
;         PG8_WAIT_V(2); PG8_BAR;
;         PG8_STAGE(PG8_SB(1, 0), cB + kstep, voffB); PG8_STAGE(PG8_SA(1, 0), cA + kstep, voffA); PG8_STAGE(PG8_SB(1, 1), cB + hstep + kstep, voffB);
;         PG8_WAIT_V(6); PG8_BAR;
.LBB0_289:
	s_add_u32 s14, s6, 0x7100000
	s_addc_u32 s15, s7, 0
	s_lshl_b32 s1, s9, 5
	s_mov_b64 s[16:17], 0x80
	s_and_b32 s9, s1, 0x60
	s_add_i32 m0, s53, 0x18000
	v_lshl_add_u64 v[6:7], v[6:7], 0, s[16:17]
	s_lshl_b32 s3, s11, 13
	s_lshl_b32 s19, s9, 7
	s_waitcnt vmcnt(2)
	s_barrier
	global_load_lds_dwordx4 v[6:7], off
	v_lshl_add_u64 v[4:5], v[4:5], 0, s[16:17]
	s_add_i32 m0, s53, 0x1a000
	s_add_i32 s58, s53, 0x8000
	s_add_i32 s59, s53, 0xa000
	global_load_lds_dwordx4 v[4:5], off
	v_lshl_add_u64 v[0:1], v[0:1], 0, s[16:17]
	s_mov_b32 m0, s58
	s_add_u32 s6, s34, 0xb0080
	global_load_lds_dwordx4 v[0:1], off
	v_lshl_add_u64 v[0:1], v[2:3], 0, s[16:17]
	s_mov_b32 m0, s59
	s_addc_u32 s7, s35, 0
	global_load_lds_dwordx4 v[0:1], off
	s_add_i32 m0, s53, 0x1c000
	v_lshl_add_u64 v[0:1], s[6:7], 0, v[130:131]
	global_load_lds_dwordx4 v[0:1], off
	v_lshl_add_u64 v[0:1], s[6:7], 0, v[134:135]
	s_add_i32 m0, s53, 0x1e000
	s_cmpk_lt_u32 s10, 0x100
	global_load_lds_dwordx4 v[0:1], off
	v_lshrrev_b32_e32 v1, 1, v8
	v_and_b32_e32 v1, 24, v1
	v_and_b32_e32 v0, 15, v8
	v_lshlrev_b32_e32 v2, 1, v1
	v_lshl_or_b32 v144, s11, 6, v0
	v_lshl_or_b32 v0, v0, 6, v2
	v_lshlrev_b32_e32 v2, 2, v8
	v_and_b32_e32 v2, 32, v2
	v_bitop3_b32 v3, v0, s3, v2 bitop3:0xde
	v_bitop3_b32 v145, v0, s19, v2 bitop3:0xde
	v_and_b32_e32 v239, 15, v8
	v_and_b32_e32 v240, 7, v239
	v_lshrrev_b32_e32 v239, 3, v239
	v_lshlrev_b32_e32 v239, 10, v239
	v_lshl_add_u32 v239, v240, 7, v239
	v_bfe_u32 v241, v8, 4, 2
	v_xor_b32_e32 v242, v241, v240
	v_or_b32_e32 v241, 4, v241
	v_xor_b32_e32 v243, v241, v240
	v_lshl_add_u32 v242, v242, 4, v239
	v_lshl_add_u32 v243, v243, 4, v239
	v_lshrrev_b32_e32 v244, 8, v8
	v_lshlrev_b32_e32 v244, 13, v244
	v_add_u32_e32 v3, v244, v242
	v_add_u32_e32 v233, v244, v243
	v_bfe_u32 v244, v8, 6, 2
	v_lshlrev_b32_e32 v244, 12, v244
	v_add_u32_e32 v145, v244, v242
	v_add_u32_e32 v234, v244, v243
	v_or_b32_e32 v146, s9, v1
	v_lshrrev_b32_e32 v1, 1, v9
	v_mul_lo_u32 v0, v11, s8
	s_mov_b32 s3, 0xb000
	v_mad_u64_u32 v[0:1], s[10:11], v1, s3, v[0:1]
	v_or_b32_e32 v0, v0, v10
	s_mov_b64 s[6:7], 0xb0080
	v_add_lshl_u32 v0, v0, v12, 1
	v_mov_b32_e32 v1, v131
	v_lshl_add_u64 v[136:137], v[0:1], 0, s[6:7]
	v_add_u32_e32 v136, 0xb0080, v128
	v_mov_b32_e32 v137, 0
	v_lshrrev_b32_e32 v1, 1, v13
	v_mul_lo_u32 v0, v14, s8
	v_mad_u64_u32 v[0:1], s[8:9], v1, s3, v[0:1]
	s_waitcnt vmcnt(6)
	v_or_b32_e32 v0, v0, v15
	s_sext_i32_i8 s1, s18
	s_cselect_b64 s[18:19], -1, 0
	v_add_lshl_u32 v0, v0, v16, 1
	v_mov_b32_e32 v1, v131
	s_add_i32 s62, 0, 0x10000
	s_add_i32 s63, 0, 0x14000
	s_ashr_i32 s60, s94, 31
	s_mov_b32 s61, s94
	v_lshl_add_u64 v[138:139], v[0:1], 0, s[6:7]
	v_add_u32_e32 v138, 0xb0080, v132
	v_mov_b32_e32 v139, 0
	v_mov_b64_e32 v[140:141], 0x200
	v_mov_b64_e32 v[142:143], 0x1ff
	v_add_u32_e32 v147, s62, v145
	v_add_u32_e32 v235, s62, v234
	v_add_u32_e32 v148, s63, v145
	v_add_u32_e32 v236, s63, v234
	v_add_u32_e32 v149, 0, v3
	v_add_u32_e32 v239, 0x18000, v145
	v_add_u32_e32 v237, 0x18000, v234
	s_mov_b64 s[20:21], 0x40000
	s_mov_b32 s64, 0x40000
	s_mov_b64 s[22:23], 0x48000
	s_mov_b32 s65, 0x48000
	s_mov_b64 s[24:25], 0x50000
	s_mov_b32 s66, 0x50000
	s_mov_b64 s[26:27], 0x58000
	s_mov_b32 s67, 0x58000
	s_barrier
	s_branch .LBB0_292

; #define PG8_STAGE(bufoff, gbase, voff) do { _Pragma("unroll") for (int _i = 0; _i < 2; ++_i) \
;         __builtin_amdgcn_global_load_lds((const unsigned*)((const char*)(gbase) + (voff)[_i]), (PG8_LAS unsigned*)(lds + (bufoff) + ldsw + _i * 8192), 16, 0, 0); } while (0)
; #define PG8_LDA(dst, b, h) do { _Pragma("unroll") for (int m = 0; m < 4; ++m) _Pragma("unroll") for (int k = 0; k < 2; ++k) dst[m][k] = *(const PG8_LAS bf16x8*)(lds + PG8_SA(b, h) + aoff + m * 2048 + k * 1024); } while (0)
; #define PG8_LDB(dst, b, h) do { _Pragma("unroll") for (int n = 0; n < 2; ++n) _Pragma("unroll") for (int k = 0; k < 2; ++k) dst[n][k] = *(const PG8_LAS bf16x8*)(lds + PG8_SB(b, h) + boff + n * 2048 + k * 1024); } while (0)
; #define PG8_MMA(ai, bj, At, Bt) do { __builtin_amdgcn_s_setprio(1); _Pragma("unroll") for (int m = 0; m < 4; ++m) _Pragma("unroll") for (int n = 0; n < 2; ++n) _Pragma("unroll") for (int k = 0; k < 2; ++k) \
;         acc[ai][bj][m][n] = __builtin_amdgcn_mfma_f32_16x16x32_bf16(Bt[n][k], At[m][k], acc[ai][bj][m][n], 0, 0, 0); __builtin_amdgcn_s_setprio(0); } while (0)
; #define PG8_WAIT_V(n) asm volatile("s_waitcnt vmcnt(" #n ")" ::: "memory")
; #define PG8_BAR __builtin_amdgcn_s_barrier()
; template <class Epi, class Sched, bool ALIGN_EPI = false, bool SP2 = false>
; __device__ __forceinline__ void gemm_phase(PG8_LAS unsigned char* lds, const Gemm g, const Sched& S, const Epi& E) {
;     ...
;         for (int t = 0; t < nt; t += 2) {
;             const bool last = (t == nt - 2);
;             const char* a1 = cA + (size_t)(t + 1) * kstep;
;             const char* a2 = last ? nA : cA + (size_t)(t + 2) * kstep; const char* b2 = last ? nB : cB + (size_t)(t + 2) * kstep;
;             const char* a3 = a2 + kstep; const char* b3 = b2 + kstep;
;             if (last && has_next) S.a_ready(nxt);
;             if constexpr (SP2) {
;             PG8_LDB(B0, 0, 0); PG8_LDB(B1, 0, 1); PG8_SCHED; PG8_LDA(At, 0, 0); PG8_STAGE(PG8_SA(1, 1), a1 + hstep, voffA);
;             PG8_WAIT_V(8); PG8_WAIT_L(0); PG8_BAR; PG8_MMA(0, 0, At, B0); PG8_MMA(0, 1, At, B1); PG8_BAR; PG8_SCHED;
;     ...
;         for (int a = 0; a < 2; ++a)
; #pragma unroll
;             for (int b = 0; b < 2; ++b)
; #pragma unroll
;                 for (int m = 0; m < 4; ++m)
; #pragma unroll
;                     for (int n = 0; n < 2; ++n) acc[a][b][m][n] = (f32x4){0.f, 0.f, 0.f, 0.f};
.LBB0_302:
	s_add_u32 s72, s34, 0x100
	v_mov_b32_e32 v0, 0
	s_addc_u32 s73, s35, 0
	s_mov_b32 s74, -2
	v_mov_b32_e32 v1, v0
	v_mov_b32_e32 v2, v0
	v_mov_b32_e32 v3, v0
	v_mov_b32_e32 v4, v0
	v_mov_b32_e32 v5, v0
	v_mov_b32_e32 v6, v0
	v_mov_b32_e32 v7, v0
	v_mov_b32_e32 v8, v0
	v_mov_b32_e32 v9, v0
	v_mov_b32_e32 v10, v0
	v_mov_b32_e32 v11, v0
	v_mov_b32_e32 v12, v0
	v_mov_b32_e32 v13, v0
	v_mov_b32_e32 v14, v0
	v_mov_b32_e32 v15, v0
	v_mov_b32_e32 v16, v0
	v_mov_b32_e32 v17, v0
	v_mov_b32_e32 v18, v0
	v_mov_b32_e32 v19, v0
	v_mov_b32_e32 v20, v0
	v_mov_b32_e32 v21, v0
	v_mov_b32_e32 v22, v0
	v_mov_b32_e32 v23, v0
	v_mov_b32_e32 v24, v0
	v_mov_b32_e32 v25, v0
	v_mov_b32_e32 v26, v0
	v_mov_b32_e32 v27, v0
	v_mov_b32_e32 v28, v0
	v_mov_b32_e32 v29, v0
	v_mov_b32_e32 v30, v0
	v_mov_b32_e32 v31, v0
	v_mov_b32_e32 v48, v0
	v_mov_b32_e32 v49, v0
	v_mov_b32_e32 v50, v0
	v_mov_b32_e32 v51, v0
	v_mov_b32_e32 v56, v0
	v_mov_b32_e32 v57, v0
	v_mov_b32_e32 v58, v0
	v_mov_b32_e32 v59, v0
	v_mov_b32_e32 v64, v0
	v_mov_b32_e32 v65, v0
	v_mov_b32_e32 v66, v0
	v_mov_b32_e32 v67, v0
	v_mov_b32_e32 v72, v0
	v_mov_b32_e32 v73, v0
	v_mov_b32_e32 v74, v0
	v_mov_b32_e32 v75, v0
	v_mov_b32_e32 v80, v0
	v_mov_b32_e32 v81, v0
	v_mov_b32_e32 v82, v0
	v_mov_b32_e32 v83, v0
	v_mov_b32_e32 v84, v0
	v_mov_b32_e32 v85, v0
	v_mov_b32_e32 v86, v0
	v_mov_b32_e32 v87, v0
	v_mov_b32_e32 v88, v0
	v_mov_b32_e32 v89, v0
	v_mov_b32_e32 v90, v0
	v_mov_b32_e32 v91, v0
	v_mov_b32_e32 v92, v0
	v_mov_b32_e32 v93, v0
	v_mov_b32_e32 v94, v0
	v_mov_b32_e32 v95, v0
	v_mov_b32_e32 v32, v0
	v_mov_b32_e32 v33, v0
	v_mov_b32_e32 v34, v0
	v_mov_b32_e32 v35, v0
	v_mov_b32_e32 v36, v0
	v_mov_b32_e32 v37, v0
	v_mov_b32_e32 v38, v0
	v_mov_b32_e32 v39, v0
	v_mov_b32_e32 v40, v0
	v_mov_b32_e32 v41, v0
	v_mov_b32_e32 v42, v0
	v_mov_b32_e32 v43, v0
	v_mov_b32_e32 v44, v0
	v_mov_b32_e32 v45, v0
	v_mov_b32_e32 v46, v0
	v_mov_b32_e32 v47, v0
	v_mov_b32_e32 v52, v0
	v_mov_b32_e32 v53, v0
	v_mov_b32_e32 v54, v0
	v_mov_b32_e32 v55, v0
	v_mov_b32_e32 v60, v0
	v_mov_b32_e32 v61, v0
	v_mov_b32_e32 v62, v0
	v_mov_b32_e32 v63, v0
	v_mov_b32_e32 v68, v0
	v_mov_b32_e32 v69, v0
	v_mov_b32_e32 v70, v0
	v_mov_b32_e32 v71, v0
	v_mov_b32_e32 v76, v0
	v_mov_b32_e32 v77, v0
	v_mov_b32_e32 v78, v0
	v_mov_b32_e32 v79, v0
	v_mov_b32_e32 v96, v0
	v_mov_b32_e32 v97, v0
	v_mov_b32_e32 v98, v0
	v_mov_b32_e32 v99, v0
	v_mov_b32_e32 v100, v0
	v_mov_b32_e32 v101, v0
	v_mov_b32_e32 v102, v0
	v_mov_b32_e32 v103, v0
	v_mov_b32_e32 v104, v0
	v_mov_b32_e32 v105, v0
	v_mov_b32_e32 v106, v0
	v_mov_b32_e32 v107, v0
	v_mov_b32_e32 v108, v0
	v_mov_b32_e32 v109, v0
	v_mov_b32_e32 v110, v0
	v_mov_b32_e32 v111, v0
	v_mov_b32_e32 v112, v0
	v_mov_b32_e32 v113, v0
	v_mov_b32_e32 v114, v0
	v_mov_b32_e32 v115, v0
	v_mov_b32_e32 v116, v0
	v_mov_b32_e32 v117, v0
	v_mov_b32_e32 v118, v0
	v_mov_b32_e32 v119, v0
	v_mov_b32_e32 v120, v0
	v_mov_b32_e32 v121, v0
	v_mov_b32_e32 v122, v0
	v_mov_b32_e32 v123, v0
	v_mov_b32_e32 v124, v0
	v_mov_b32_e32 v125, v0
	v_mov_b32_e32 v126, v0
	v_mov_b32_e32 v127, v0
	ds_read_b128 v[150:153], v147
	ds_read_b128 v[154:157], v235
	ds_read_b128 v[158:161], v147 offset:2048
	ds_read_b128 v[162:165], v235 offset:2048
.LBB0_303:
	ds_read_b128 v[166:169], v148
	ds_read_b128 v[170:173], v236
	ds_read_b128 v[174:177], v148 offset:2048
	ds_read_b128 v[178:181], v236 offset:2048
	s_add_u32 s34, s30, 0x100
	s_addc_u32 s35, s31, 0
	s_cmp_eq_u32 s74, 40
	s_cselect_b32 s39, s9, s35
	s_cselect_b32 s38, s8, s34
	s_cselect_b32 s37, s29, s73
	s_cselect_b32 s36, s28, s72
	v_lshl_add_u64 v[222:223], s[30:31], 0, v[136:137]
	s_add_i32 m0, s53, 0xc000
	ds_read_b128 v[190:193], v149
	ds_read_b128 v[194:197], v233
	ds_read_b128 v[198:201], v149 offset:2048
	ds_read_b128 v[202:205], v233 offset:2048
	ds_read_b128 v[206:209], v149 offset:4096
	ds_read_b128 v[210:213], v233 offset:4096
	ds_read_b128 v[214:217], v149 offset:6144
	ds_read_b128 v[218:221], v233 offset:6144
	global_load_lds_dwordx4 v[222:223], off
	v_lshl_add_u64 v[222:223], s[30:31], 0, v[138:139]
	s_add_i32 m0, s53, 0xe000
	s_nop 0
	global_load_lds_dwordx4 v[222:223], off
	s_waitcnt vmcnt(8)
	s_waitcnt lgkmcnt(0)
	s_barrier
	s_setprio 1
	s_waitcnt lgkmcnt(0)
	v_mfma_f32_16x16x32_bf16 v[124:127], v[150:153], v[190:193], v[124:127]
	v_mfma_f32_16x16x32_bf16 v[120:123], v[158:161], v[190:193], v[120:123]
	v_mfma_f32_16x16x32_bf16 v[116:119], v[150:153], v[198:201], v[116:119]
	v_mfma_f32_16x16x32_bf16 v[112:115], v[158:161], v[198:201], v[112:115]
	v_mfma_f32_16x16x32_bf16 v[108:111], v[150:153], v[206:209], v[108:111]
	v_mfma_f32_16x16x32_bf16 v[104:107], v[158:161], v[206:209], v[104:107]
	v_mfma_f32_16x16x32_bf16 v[100:103], v[150:153], v[214:217], v[100:103]
	v_mfma_f32_16x16x32_bf16 v[96:99], v[158:161], v[214:217], v[96:99]
	v_mfma_f32_16x16x32_bf16 v[124:127], v[154:157], v[194:197], v[124:127]
	v_mfma_f32_16x16x32_bf16 v[120:123], v[162:165], v[194:197], v[120:123]
	v_mfma_f32_16x16x32_bf16 v[116:119], v[154:157], v[202:205], v[116:119]
	v_mfma_f32_16x16x32_bf16 v[112:115], v[162:165], v[202:205], v[112:115]
	v_mfma_f32_16x16x32_bf16 v[108:111], v[154:157], v[210:213], v[108:111]
	v_mfma_f32_16x16x32_bf16 v[104:107], v[162:165], v[210:213], v[104:107]
	v_mfma_f32_16x16x32_bf16 v[100:103], v[154:157], v[218:221], v[100:103]
	v_mfma_f32_16x16x32_bf16 v[96:99], v[162:165], v[218:221], v[96:99]
	s_setprio 0
	s_setprio 1
	v_mfma_f32_16x16x32_bf16 v[76:79], v[166:169], v[190:193], v[76:79]
	v_mfma_f32_16x16x32_bf16 v[68:71], v[174:177], v[190:193], v[68:71]
	v_mfma_f32_16x16x32_bf16 v[60:63], v[166:169], v[198:201], v[60:63]
	v_mfma_f32_16x16x32_bf16 v[52:55], v[174:177], v[198:201], v[52:55]
	v_mfma_f32_16x16x32_bf16 v[44:47], v[166:169], v[206:209], v[44:47]
	v_mfma_f32_16x16x32_bf16 v[40:43], v[174:177], v[206:209], v[40:43]
	v_mfma_f32_16x16x32_bf16 v[36:39], v[166:169], v[214:217], v[36:39]
	v_mfma_f32_16x16x32_bf16 v[32:35], v[174:177], v[214:217], v[32:35]
	v_mfma_f32_16x16x32_bf16 v[76:79], v[170:173], v[194:197], v[76:79]
	v_mfma_f32_16x16x32_bf16 v[68:71], v[178:181], v[194:197], v[68:71]
	v_mfma_f32_16x16x32_bf16 v[60:63], v[170:173], v[202:205], v[60:63]
	v_mfma_f32_16x16x32_bf16 v[52:55], v[178:181], v[202:205], v[52:55]
	v_mfma_f32_16x16x32_bf16 v[44:47], v[170:173], v[210:213], v[44:47]
	v_mfma_f32_16x16x32_bf16 v[40:43], v[178:181], v[210:213], v[40:43]
	v_mfma_f32_16x16x32_bf16 v[36:39], v[170:173], v[218:221], v[36:39]
	v_mfma_f32_16x16x32_bf16 v[32:35], v[178:181], v[218:221], v[32:35]
	s_setprio 0
	s_barrier
; #define PG8_STAGE(bufoff, gbase, voff) do { _Pragma("unroll") for (int _i = 0; _i < 2; ++_i) \
;         __builtin_amdgcn_global_load_lds((const unsigned*)((const char*)(gbase) + (voff)[_i]), (PG8_LAS unsigned*)(lds + (bufoff) + ldsw + _i * 8192), 16, 0, 0); } while (0)
; #define PG8_LDA(dst, b, h) do { _Pragma("unroll") for (int m = 0; m < 4; ++m) _Pragma("unroll") for (int k = 0; k < 2; ++k) dst[m][k] = *(const PG8_LAS bf16x8*)(lds + PG8_SA(b, h) + aoff + m * 2048 + k * 1024); } while (0)
; #define PG8_LDB(dst, b, h) do { _Pragma("unroll") for (int n = 0; n < 2; ++n) _Pragma("unroll") for (int k = 0; k < 2; ++k) dst[n][k] = *(const PG8_LAS bf16x8*)(lds + PG8_SB(b, h) + boff + n * 2048 + k * 1024); } while (0)
; #define PG8_MMA(ai, bj, At, Bt) do { __builtin_amdgcn_s_setprio(1); _Pragma("unroll") for (int m = 0; m < 4; ++m) _Pragma("unroll") for (int n = 0; n < 2; ++n) _Pragma("unroll") for (int k = 0; k < 2; ++k) \
;         acc[ai][bj][m][n] = __builtin_amdgcn_mfma_f32_16x16x32_bf16(Bt[n][k], At[m][k], acc[ai][bj][m][n], 0, 0, 0); __builtin_amdgcn_s_setprio(0); } while (0)
; #define PG8_WAIT_V(n) asm volatile("s_waitcnt vmcnt(" #n ")" ::: "memory")
; #define PG8_WAIT_L(n) asm volatile("s_waitcnt lgkmcnt(" #n ")" ::: "memory")
; #define PG8_BAR __builtin_amdgcn_s_barrier()
; #define PG8_SCHED __builtin_amdgcn_sched_barrier(0)
; template <class Epi, class Sched, bool ALIGN_EPI = false, bool SP2 = false>
; __device__ __forceinline__ void gemm_phase(PG8_LAS unsigned char* lds, const Gemm g, const Sched& S, const Epi& E) {
;     ...
;             PG8_LDA(At, 0, 1); PG8_STAGE(PG8_SB(0, 0), b2, voffB); PG8_STAGE(PG8_SB(0, 1), b2 + hstep, voffB); PG8_STAGE(PG8_SA(0, 0), a2, voffA);
;             PG8_WAIT_V(8); PG8_WAIT_L(0); PG8_BAR; PG8_MMA(1, 0, At, B0); PG8_MMA(1, 1, At, B1); PG8_BAR; PG8_SCHED;
;             PG8_LDB(B0, 1, 0); PG8_LDB(B1, 1, 1); PG8_SCHED; PG8_LDA(At, 1, 0); PG8_STAGE(PG8_SA(0, 1), a2 + hstep, voffA);
	s_add_i32 s3, s62, s52
	v_lshl_add_u64 v[222:223], s[36:37], 0, v[130:131]
	s_mov_b32 m0, s3
	ds_read_b128 v[190:193], v149 offset:16384
	ds_read_b128 v[194:197], v233 offset:16384
	ds_read_b128 v[198:201], v149 offset:18432
	ds_read_b128 v[202:205], v233 offset:18432
	ds_read_b128 v[206:209], v149 offset:20480
	ds_read_b128 v[210:213], v233 offset:20480
	ds_read_b128 v[214:217], v149 offset:22528
	ds_read_b128 v[218:221], v233 offset:22528
	global_load_lds_dwordx4 v[222:223], off
	s_add_i32 m0, s3, 0x2000
	s_add_u32 s10, s36, 0xb0000
	v_lshl_add_u64 v[224:225], s[36:37], 0, v[134:135]
	s_addc_u32 s11, s37, 0
	s_add_i32 s3, s63, s52
	global_load_lds_dwordx4 v[224:225], off
	v_lshl_add_u64 v[226:227], s[10:11], 0, v[130:131]
	s_mov_b32 m0, s3
	v_lshl_add_u64 v[228:229], s[38:39], 0, v[132:133]
	global_load_lds_dwordx4 v[226:227], off
	v_lshl_add_u64 v[226:227], s[10:11], 0, v[134:135]
	s_add_i32 m0, s3, 0x2000
	s_nop 0
	global_load_lds_dwordx4 v[226:227], off
	v_lshl_add_u64 v[226:227], s[38:39], 0, v[128:129]
	s_mov_b32 m0, s53
	s_nop 0
	global_load_lds_dwordx4 v[226:227], off
	s_mov_b32 m0, s54
	s_nop 0
	global_load_lds_dwordx4 v[228:229], off
	s_waitcnt vmcnt(8)
	s_waitcnt lgkmcnt(0)
	s_barrier
	s_setprio 1
	s_waitcnt lgkmcnt(0)
	ds_read_b128 v[240:243], v239
	ds_read_b128 v[244:247], v237
	ds_read_b128 v[248:251], v239 offset:2048
	ds_read_b128 v[252:255], v237 offset:2048
	v_mfma_f32_16x16x32_bf16 v[92:95], v[150:153], v[190:193], v[92:95]
	v_mfma_f32_16x16x32_bf16 v[88:91], v[158:161], v[190:193], v[88:91]
	v_mfma_f32_16x16x32_bf16 v[84:87], v[150:153], v[198:201], v[84:87]
	v_mfma_f32_16x16x32_bf16 v[80:83], v[158:161], v[198:201], v[80:83]
	v_mfma_f32_16x16x32_bf16 v[72:75], v[150:153], v[206:209], v[72:75]
	v_mfma_f32_16x16x32_bf16 v[64:67], v[158:161], v[206:209], v[64:67]
	v_mfma_f32_16x16x32_bf16 v[56:59], v[150:153], v[214:217], v[56:59]
	v_mfma_f32_16x16x32_bf16 v[48:51], v[158:161], v[214:217], v[48:51]
	v_mfma_f32_16x16x32_bf16 v[92:95], v[154:157], v[194:197], v[92:95]
	v_mfma_f32_16x16x32_bf16 v[88:91], v[162:165], v[194:197], v[88:91]
	v_mfma_f32_16x16x32_bf16 v[84:87], v[154:157], v[202:205], v[84:87]
	v_mfma_f32_16x16x32_bf16 v[80:83], v[162:165], v[202:205], v[80:83]
	v_mfma_f32_16x16x32_bf16 v[72:75], v[154:157], v[210:213], v[72:75]
	v_mfma_f32_16x16x32_bf16 v[64:67], v[162:165], v[210:213], v[64:67]
	v_mfma_f32_16x16x32_bf16 v[56:59], v[154:157], v[218:221], v[56:59]
	v_mfma_f32_16x16x32_bf16 v[48:51], v[162:165], v[218:221], v[48:51]
	s_setprio 0
	s_setprio 1
	v_mfma_f32_16x16x32_bf16 v[28:31], v[166:169], v[190:193], v[28:31]
	v_mfma_f32_16x16x32_bf16 v[24:27], v[174:177], v[190:193], v[24:27]
	v_mfma_f32_16x16x32_bf16 v[20:23], v[166:169], v[198:201], v[20:23]
	v_mfma_f32_16x16x32_bf16 v[16:19], v[174:177], v[198:201], v[16:19]
	v_mfma_f32_16x16x32_bf16 v[12:15], v[166:169], v[206:209], v[12:15]
	v_mfma_f32_16x16x32_bf16 v[8:11], v[174:177], v[206:209], v[8:11]
	v_mfma_f32_16x16x32_bf16 v[4:7], v[166:169], v[214:217], v[4:7]
	v_mfma_f32_16x16x32_bf16 v[0:3], v[174:177], v[214:217], v[0:3]
	v_mfma_f32_16x16x32_bf16 v[28:31], v[170:173], v[194:197], v[28:31]
	v_mfma_f32_16x16x32_bf16 v[24:27], v[178:181], v[194:197], v[24:27]
	v_mfma_f32_16x16x32_bf16 v[20:23], v[170:173], v[202:205], v[20:23]
	v_mfma_f32_16x16x32_bf16 v[16:19], v[178:181], v[202:205], v[16:19]
	v_mfma_f32_16x16x32_bf16 v[12:15], v[170:173], v[210:213], v[12:15]
	v_mfma_f32_16x16x32_bf16 v[8:11], v[178:181], v[210:213], v[8:11]
	v_mfma_f32_16x16x32_bf16 v[4:7], v[170:173], v[218:221], v[4:7]
	v_mfma_f32_16x16x32_bf16 v[0:3], v[178:181], v[218:221], v[0:3]
	s_setprio 0
	s_barrier
	s_add_i32 s3, 0, 0x18000
	s_add_i32 s30, 0, 0x1c000
	v_add_u32_e32 v178, s30, v145
	v_add_u32_e32 v238, s30, v234
	ds_read_b128 v[166:169], v178
	ds_read_b128 v[170:173], v238
	ds_read_b128 v[174:177], v178 offset:2048
	ds_read_b128 v[178:181], v238 offset:2048
	s_add_u32 s10, s38, 0xb0000
	s_addc_u32 s11, s39, 0
	s_mov_b32 m0, s55
	v_lshl_add_u64 v[230:231], s[10:11], 0, v[128:129]
	ds_read_b128 v[190:193], v149 offset:32768
	ds_read_b128 v[194:197], v233 offset:32768
	ds_read_b128 v[198:201], v149 offset:34816
	ds_read_b128 v[202:205], v233 offset:34816
	ds_read_b128 v[206:209], v149 offset:36864
	ds_read_b128 v[210:213], v233 offset:36864
	ds_read_b128 v[214:217], v149 offset:38912
	ds_read_b128 v[218:221], v233 offset:38912
	global_load_lds_dwordx4 v[230:231], off
	v_lshl_add_u64 v[230:231], s[10:11], 0, v[132:133]
	s_mov_b32 m0, s56
	s_nop 0
	global_load_lds_dwordx4 v[230:231], off
	s_waitcnt vmcnt(8)
	s_waitcnt lgkmcnt(0)
	s_barrier
; #define PG8_STAGE(bufoff, gbase, voff) do { _Pragma("unroll") for (int _i = 0; _i < 2; ++_i) \
;         __builtin_amdgcn_global_load_lds((const unsigned*)((const char*)(gbase) + (voff)[_i]), (PG8_LAS unsigned*)(lds + (bufoff) + ldsw + _i * 8192), 16, 0, 0); } while (0)
; #define PG8_LDA(dst, b, h) do { _Pragma("unroll") for (int m = 0; m < 4; ++m) _Pragma("unroll") for (int k = 0; k < 2; ++k) dst[m][k] = *(const PG8_LAS bf16x8*)(lds + PG8_SA(b, h) + aoff + m * 2048 + k * 1024); } while (0)
; #define PG8_LDB(dst, b, h) do { _Pragma("unroll") for (int n = 0; n < 2; ++n) _Pragma("unroll") for (int k = 0; k < 2; ++k) dst[n][k] = *(const PG8_LAS bf16x8*)(lds + PG8_SB(b, h) + boff + n * 2048 + k * 1024); } while (0)
; #define PG8_MMA(ai, bj, At, Bt) do { __builtin_amdgcn_s_setprio(1); _Pragma("unroll") for (int m = 0; m < 4; ++m) _Pragma("unroll") for (int n = 0; n < 2; ++n) _Pragma("unroll") for (int k = 0; k < 2; ++k) \
;         acc[ai][bj][m][n] = __builtin_amdgcn_mfma_f32_16x16x32_bf16(Bt[n][k], At[m][k], acc[ai][bj][m][n], 0, 0, 0); __builtin_amdgcn_s_setprio(0); } while (0)
; #define PG8_WAIT_V(n) asm volatile("s_waitcnt vmcnt(" #n ")" ::: "memory")
; #define PG8_WAIT_L(n) asm volatile("s_waitcnt lgkmcnt(" #n ")" ::: "memory")
; #define PG8_BAR __builtin_amdgcn_s_barrier()
; #define PG8_SCHED __builtin_amdgcn_sched_barrier(0)
; template <class Epi, class Sched, bool ALIGN_EPI = false, bool SP2 = false>
; __device__ __forceinline__ void gemm_phase(PG8_LAS unsigned char* lds, const Gemm g, const Sched& S, const Epi& E) {
;     ...
;             PG8_LDB(B0, 1, 0); PG8_LDB(B1, 1, 1); PG8_SCHED; PG8_LDA(At, 1, 0); PG8_STAGE(PG8_SA(0, 1), a2 + hstep, voffA);
;             PG8_WAIT_V(8); PG8_WAIT_L(0); PG8_BAR; PG8_MMA(0, 0, At, B0); PG8_MMA(0, 1, At, B1); PG8_BAR; PG8_SCHED;
;             PG8_LDA(At, 1, 1); PG8_STAGE(PG8_SB(1, 0), b3, voffB); PG8_STAGE(PG8_SB(1, 1), b3 + hstep, voffB); PG8_STAGE(PG8_SA(1, 0), a3, voffA);
;             PG8_WAIT_V(8); PG8_WAIT_L(0); PG8_BAR; PG8_MMA(1, 0, At, B0); PG8_MMA(1, 1, At, B1); PG8_BAR; PG8_SCHED;
	s_setprio 1
	s_waitcnt lgkmcnt(0)
	v_mfma_f32_16x16x32_bf16 v[124:127], v[240:243], v[190:193], v[124:127]
	v_mfma_f32_16x16x32_bf16 v[120:123], v[248:251], v[190:193], v[120:123]
	v_mfma_f32_16x16x32_bf16 v[116:119], v[240:243], v[198:201], v[116:119]
	v_mfma_f32_16x16x32_bf16 v[112:115], v[248:251], v[198:201], v[112:115]
	v_mfma_f32_16x16x32_bf16 v[108:111], v[240:243], v[206:209], v[108:111]
	v_mfma_f32_16x16x32_bf16 v[104:107], v[248:251], v[206:209], v[104:107]
	v_mfma_f32_16x16x32_bf16 v[100:103], v[240:243], v[214:217], v[100:103]
	v_mfma_f32_16x16x32_bf16 v[96:99], v[248:251], v[214:217], v[96:99]
	v_mfma_f32_16x16x32_bf16 v[124:127], v[244:247], v[194:197], v[124:127]
	v_mfma_f32_16x16x32_bf16 v[120:123], v[252:255], v[194:197], v[120:123]
	v_mfma_f32_16x16x32_bf16 v[116:119], v[244:247], v[202:205], v[116:119]
	v_mfma_f32_16x16x32_bf16 v[112:115], v[252:255], v[202:205], v[112:115]
	v_mfma_f32_16x16x32_bf16 v[108:111], v[244:247], v[210:213], v[108:111]
	v_mfma_f32_16x16x32_bf16 v[104:107], v[252:255], v[210:213], v[104:107]
	v_mfma_f32_16x16x32_bf16 v[100:103], v[244:247], v[218:221], v[100:103]
	v_mfma_f32_16x16x32_bf16 v[96:99], v[252:255], v[218:221], v[96:99]
	s_setprio 0
	s_setprio 1
	v_mfma_f32_16x16x32_bf16 v[76:79], v[166:169], v[190:193], v[76:79]
	v_mfma_f32_16x16x32_bf16 v[68:71], v[174:177], v[190:193], v[68:71]
	v_mfma_f32_16x16x32_bf16 v[60:63], v[166:169], v[198:201], v[60:63]
	v_mfma_f32_16x16x32_bf16 v[52:55], v[174:177], v[198:201], v[52:55]
	v_mfma_f32_16x16x32_bf16 v[44:47], v[166:169], v[206:209], v[44:47]
	v_mfma_f32_16x16x32_bf16 v[40:43], v[174:177], v[206:209], v[40:43]
	v_mfma_f32_16x16x32_bf16 v[36:39], v[166:169], v[214:217], v[36:39]
	v_mfma_f32_16x16x32_bf16 v[32:35], v[174:177], v[214:217], v[32:35]
	v_mfma_f32_16x16x32_bf16 v[76:79], v[170:173], v[194:197], v[76:79]
	v_mfma_f32_16x16x32_bf16 v[68:71], v[178:181], v[194:197], v[68:71]
	v_mfma_f32_16x16x32_bf16 v[60:63], v[170:173], v[202:205], v[60:63]
	v_mfma_f32_16x16x32_bf16 v[52:55], v[178:181], v[202:205], v[52:55]
	v_mfma_f32_16x16x32_bf16 v[44:47], v[170:173], v[210:213], v[44:47]
	v_mfma_f32_16x16x32_bf16 v[40:43], v[178:181], v[210:213], v[40:43]
	v_mfma_f32_16x16x32_bf16 v[36:39], v[170:173], v[218:221], v[36:39]
	v_mfma_f32_16x16x32_bf16 v[32:35], v[178:181], v[218:221], v[32:35]
	s_setprio 0
	s_barrier
	s_add_i32 s3, s3, s52
	v_lshl_add_u64 v[222:223], v[222:223], 0, s[16:17]
	s_mov_b32 m0, s3
	ds_read_b128 v[190:193], v149 offset:49152
	ds_read_b128 v[194:197], v233 offset:49152
	ds_read_b128 v[198:201], v149 offset:51200
	ds_read_b128 v[202:205], v233 offset:51200
	ds_read_b128 v[206:209], v149 offset:53248
	ds_read_b128 v[210:213], v233 offset:53248
	ds_read_b128 v[214:217], v149 offset:55296
	ds_read_b128 v[218:221], v233 offset:55296
	global_load_lds_dwordx4 v[222:223], off
	s_add_i32 m0, s3, 0x2000
	s_add_u32 s10, s36, 0xb0080
	v_lshl_add_u64 v[222:223], v[224:225], 0, s[16:17]
	s_addc_u32 s11, s37, 0
	s_add_i32 s3, s30, s52
	global_load_lds_dwordx4 v[222:223], off
	v_lshl_add_u64 v[222:223], s[10:11], 0, v[130:131]
	s_mov_b32 m0, s3
	s_nop 0
	global_load_lds_dwordx4 v[222:223], off
	v_lshl_add_u64 v[222:223], s[10:11], 0, v[134:135]
	s_add_i32 m0, s3, 0x2000
	s_nop 0
	global_load_lds_dwordx4 v[222:223], off
	v_lshl_add_u64 v[222:223], v[226:227], 0, s[16:17]
	s_mov_b32 m0, s58
	s_nop 0
	global_load_lds_dwordx4 v[222:223], off
	v_lshl_add_u64 v[222:223], v[228:229], 0, s[16:17]
	s_mov_b32 m0, s59
	s_nop 0
	global_load_lds_dwordx4 v[222:223], off
	s_waitcnt vmcnt(8)
	s_waitcnt lgkmcnt(0)
	s_barrier
	s_setprio 1
	s_waitcnt lgkmcnt(0)
	ds_read_b128 v[150:153], v147
	ds_read_b128 v[154:157], v235
	ds_read_b128 v[158:161], v147 offset:2048
	ds_read_b128 v[162:165], v235 offset:2048
	v_mfma_f32_16x16x32_bf16 v[92:95], v[240:243], v[190:193], v[92:95]
	v_mfma_f32_16x16x32_bf16 v[88:91], v[248:251], v[190:193], v[88:91]
	v_mfma_f32_16x16x32_bf16 v[84:87], v[240:243], v[198:201], v[84:87]
	v_mfma_f32_16x16x32_bf16 v[80:83], v[248:251], v[198:201], v[80:83]
	v_mfma_f32_16x16x32_bf16 v[72:75], v[240:243], v[206:209], v[72:75]
	v_mfma_f32_16x16x32_bf16 v[64:67], v[248:251], v[206:209], v[64:67]
	v_mfma_f32_16x16x32_bf16 v[56:59], v[240:243], v[214:217], v[56:59]
	v_mfma_f32_16x16x32_bf16 v[48:51], v[248:251], v[214:217], v[48:51]
	v_mfma_f32_16x16x32_bf16 v[92:95], v[244:247], v[194:197], v[92:95]
	v_mfma_f32_16x16x32_bf16 v[88:91], v[252:255], v[194:197], v[88:91]
	v_mfma_f32_16x16x32_bf16 v[84:87], v[244:247], v[202:205], v[84:87]
	v_mfma_f32_16x16x32_bf16 v[80:83], v[252:255], v[202:205], v[80:83]
	v_mfma_f32_16x16x32_bf16 v[72:75], v[244:247], v[210:213], v[72:75]
	v_mfma_f32_16x16x32_bf16 v[64:67], v[252:255], v[210:213], v[64:67]
	v_mfma_f32_16x16x32_bf16 v[56:59], v[244:247], v[218:221], v[56:59]
	v_mfma_f32_16x16x32_bf16 v[48:51], v[252:255], v[218:221], v[48:51]
	s_setprio 0
	s_setprio 1
	v_mfma_f32_16x16x32_bf16 v[28:31], v[166:169], v[190:193], v[28:31]
	v_mfma_f32_16x16x32_bf16 v[24:27], v[174:177], v[190:193], v[24:27]
	v_mfma_f32_16x16x32_bf16 v[20:23], v[166:169], v[198:201], v[20:23]
	v_mfma_f32_16x16x32_bf16 v[16:19], v[174:177], v[198:201], v[16:19]
	v_mfma_f32_16x16x32_bf16 v[12:15], v[166:169], v[206:209], v[12:15]
	v_mfma_f32_16x16x32_bf16 v[8:11], v[174:177], v[206:209], v[8:11]
	v_mfma_f32_16x16x32_bf16 v[4:7], v[166:169], v[214:217], v[4:7]
	v_mfma_f32_16x16x32_bf16 v[0:3], v[174:177], v[214:217], v[0:3]
	v_mfma_f32_16x16x32_bf16 v[28:31], v[170:173], v[194:197], v[28:31]
	v_mfma_f32_16x16x32_bf16 v[24:27], v[178:181], v[194:197], v[24:27]
	v_mfma_f32_16x16x32_bf16 v[20:23], v[170:173], v[202:205], v[20:23]
	v_mfma_f32_16x16x32_bf16 v[16:19], v[178:181], v[202:205], v[16:19]
	v_mfma_f32_16x16x32_bf16 v[12:15], v[170:173], v[210:213], v[12:15]
	v_mfma_f32_16x16x32_bf16 v[8:11], v[178:181], v[210:213], v[8:11]
	v_mfma_f32_16x16x32_bf16 v[4:7], v[170:173], v[218:221], v[4:7]
	v_mfma_f32_16x16x32_bf16 v[0:3], v[178:181], v[218:221], v[0:3]
	s_setprio 0
	s_barrier
	s_add_i32 s74, s74, 2
	s_add_u32 s72, s72, 0x100
	s_addc_u32 s73, s73, 0
	s_cmp_gt_u32 s74, 41
	s_mov_b64 s[30:31], s[34:35]
	s_cbranch_scc0 .LBB0_303
	s_waitcnt lgkmcnt(0)
	s_and_b64 vcc, exec, s[18:19]
	s_cbranch_vccz .LBB0_306
	s_barrier

; __device__ __forceinline__ int fresh_tid() { int t = (int)threadIdx.x; asm volatile("" : "+v"(t)); return t; }
; #define PG8_STAGE(bufoff, gbase, voff) do { _Pragma("unroll") for (int _i = 0; _i < 2; ++_i) \
;         __builtin_amdgcn_global_load_lds((const unsigned*)((const char*)(gbase) + (voff)[_i]), (PG8_LAS unsigned*)(lds + (bufoff) + ldsw + _i * 8192), 16, 0, 0); } while (0)
; template <class Epi, class Sched, bool ALIGN_EPI = false, bool SP2 = false>
; __device__ __forceinline__ void gemm_phase(PG8_LAS unsigned char* lds, const Gemm g, const Sched& S, const Epi& E) {
;     const int tid = fresh_tid(), wid = __builtin_amdgcn_readfirstlane(tid >> 6), lane = tid & 63, wr = wid >> 2, wc = wid & 3, fr = lane & 15, fq = lane >> 4;
;     const int K = g.K, nt = K / BK;
;     unsigned voffA[2], voffB[2];
; #pragma unroll
;     for (int i = 0; i < 2; ++i) { int R, C; stage_rc(tid * 16 + i * 8192, R, C); const int Rb = Epi::PERM ? ((R & ~31) + perm32(R & 31)) : R;
;         voffA[i] = (unsigned)(R * K + C) * 2u; voffB[i] = (unsigned)(Rb * K + C) * 2u; }
;     const size_t kstep = (size_t)(BK * 2);
;     const size_t hstep = (size_t)HALF * K * 2;
;     const size_t tstep = 2 * hstep;
;     const unsigned ldsw = (unsigned)wid * 1024u;
;     const int aoff = lds_byte(wr * 64 + fr, fq * 8), boff = lds_byte(wc * 32 + fr, fq * 8);
;     ...
;     Unit cur, nxt; int ui = 0;
;     if (!S.next(0, cur)) return;
;     f32x4 acc[2][2][4][2];
; #pragma unroll
;     for (int a = 0; a < 2; ++a)
; #pragma unroll
;         for (int b = 0; b < 2; ++b)
; #pragma unroll
;             for (int m = 0; m < 4; ++m)
; #pragma unroll
;                 for (int n = 0; n < 2; ++n) acc[a][b][m][n] = (f32x4){0.f, 0.f, 0.f, 0.f};
;     bf16x8 At[4][2], B0[2][2], B1[2][2];
;     const char* cA = (const char*)g.A + (size_t)cur.pm * tstep; const char* cB = (const char*)g.Bt + (size_t)cur.pn * tstep;
;     S.a_ready(cur);
;     if constexpr (SP2) {
;         PG8_STAGE(PG8_SB(0, 0), cB, voffB); PG8_STAGE(PG8_SB(0, 1), cB + hstep, voffB); PG8_STAGE(PG8_SA(0, 0), cA, voffA); PG8_STAGE(PG8_SA(0, 1), cA + hstep, voffA);
;         if (wr == 1) PG8_BAR;
;         PG8_WAIT_V(2); PG8_BAR;
;         PG8_STAGE(PG8_SB(1, 0), cB + kstep, voffB); PG8_STAGE(PG8_SA(1, 0), cA + kstep, voffA); PG8_STAGE(PG8_SB(1, 1), cB + hstep + kstep, voffB);
;         PG8_WAIT_V(6); PG8_BAR;
.LBB0_1195:
	s_add_u32 s12, s4, 0x7100000
	s_addc_u32 s13, s5, 0
	s_lshl_b32 s0, s9, 5
	s_mov_b64 s[14:15], 0x80
	s_and_b32 s4, s0, 0x60
	s_add_i32 m0, s47, 0x18000
	v_lshl_add_u64 v[6:7], v[6:7], 0, s[14:15]
	s_lshl_b32 s3, s17, 13
	s_lshl_b32 s5, s4, 7
	s_waitcnt vmcnt(2)
	s_barrier
	global_load_lds_dwordx4 v[6:7], off
	v_lshl_add_u64 v[4:5], v[4:5], 0, s[14:15]
	s_add_i32 m0, s47, 0x1a000
	s_add_i32 s52, s47, 0x8000
	s_add_i32 s53, s47, 0xa000
	global_load_lds_dwordx4 v[4:5], off
	v_lshl_add_u64 v[0:1], v[0:1], 0, s[14:15]
	s_mov_b32 m0, s52
	s_add_u32 s0, s30, 0xb0080
	global_load_lds_dwordx4 v[0:1], off
	v_lshl_add_u64 v[0:1], v[2:3], 0, s[14:15]
	s_mov_b32 m0, s53
	s_addc_u32 s1, s31, 0
	global_load_lds_dwordx4 v[0:1], off
	s_add_i32 m0, s47, 0x1c000
	v_lshl_add_u64 v[0:1], s[0:1], 0, v[130:131]
	global_load_lds_dwordx4 v[0:1], off
	v_lshl_add_u64 v[0:1], s[0:1], 0, v[134:135]
	s_add_i32 m0, s47, 0x1e000
	s_mov_b64 s[0:1], 0xb0080
	global_load_lds_dwordx4 v[0:1], off
	v_lshrrev_b32_e32 v1, 1, v8
	v_and_b32_e32 v1, 24, v1
	v_and_b32_e32 v0, 15, v8
	v_lshlrev_b32_e32 v2, 1, v1
	v_lshl_or_b32 v144, s17, 6, v0
	v_lshl_or_b32 v0, v0, 6, v2
	v_lshlrev_b32_e32 v2, 2, v8
	v_and_b32_e32 v2, 32, v2
	v_bitop3_b32 v3, v0, s3, v2 bitop3:0xde
	v_bitop3_b32 v145, v0, s5, v2 bitop3:0xde
	v_and_b32_e32 v239, 15, v8
	v_and_b32_e32 v240, 7, v239
	v_lshrrev_b32_e32 v239, 3, v239
	v_lshlrev_b32_e32 v239, 10, v239
	v_lshl_add_u32 v239, v240, 7, v239
	v_bfe_u32 v241, v8, 4, 2
	v_xor_b32_e32 v242, v241, v240
	v_or_b32_e32 v241, 4, v241
	v_xor_b32_e32 v243, v241, v240
	v_lshl_add_u32 v242, v242, 4, v239
	v_lshl_add_u32 v243, v243, 4, v239
	v_lshrrev_b32_e32 v244, 8, v8
	v_lshlrev_b32_e32 v244, 13, v244
	v_add_u32_e32 v3, v244, v242
	v_add_u32_e32 v233, v244, v243
	v_bfe_u32 v244, v8, 6, 2
	v_lshlrev_b32_e32 v244, 12, v244
	v_add_u32_e32 v145, v244, v242
	v_add_u32_e32 v234, v244, v243
	v_or_b32_e32 v146, s4, v1
	v_lshrrev_b32_e32 v1, 1, v9
	v_mul_lo_u32 v0, v11, s8
	s_mov_b32 s3, 0xb000
	v_mad_u64_u32 v[0:1], s[4:5], v1, s3, v[0:1]
	v_or_b32_e32 v0, v0, v10
	v_add_lshl_u32 v0, v0, v12, 1
	v_mov_b32_e32 v1, v131
	v_lshl_add_u64 v[136:137], v[0:1], 0, s[0:1]
	v_add_u32_e32 v136, 0xb0080, v128
	v_mov_b32_e32 v137, 0
	v_lshrrev_b32_e32 v1, 1, v13
	v_mul_lo_u32 v0, v14, s8
	v_mad_u64_u32 v[0:1], s[4:5], v1, s3, v[0:1]
	s_waitcnt vmcnt(6)
	s_cmpk_lt_u32 s16, 0x100
	v_or_b32_e32 v0, v0, v15
	s_cselect_b64 s[16:17], -1, 0
	v_add_lshl_u32 v0, v0, v16, 1
	v_mov_b32_e32 v1, v131
	s_add_i32 s56, 0, 0x10000
	s_add_i32 s57, 0, 0x14000
	s_sext_i32_i8 s65, s18
	s_ashr_i32 s54, s94, 31
	s_mov_b32 s55, s94
	v_lshl_add_u64 v[138:139], v[0:1], 0, s[0:1]
	v_add_u32_e32 v138, 0xb0080, v132
	v_mov_b32_e32 v139, 0
	v_mov_b64_e32 v[140:141], 0x200
	v_mov_b64_e32 v[142:143], 0x1ff
	v_add_u32_e32 v147, s56, v145
	v_add_u32_e32 v235, s56, v234
	v_add_u32_e32 v148, s57, v145
	v_add_u32_e32 v236, s57, v234
	v_add_u32_e32 v149, 0, v3
	v_add_u32_e32 v239, 0x18000, v145
	v_add_u32_e32 v237, 0x18000, v234
	s_mov_b64 s[18:19], 0x40000
	s_mov_b32 s58, 0x40000
	s_mov_b64 s[20:21], 0x48000
	s_mov_b32 s59, 0x48000
	s_mov_b64 s[22:23], 0x50000
	s_mov_b32 s60, 0x50000
	s_mov_b64 s[24:25], 0x58000
	s_mov_b32 s61, 0x58000
	s_barrier
	s_branch .LBB0_1198

; #define PG8_STAGE(bufoff, gbase, voff) do { _Pragma("unroll") for (int _i = 0; _i < 2; ++_i) \
;         __builtin_amdgcn_global_load_lds((const unsigned*)((const char*)(gbase) + (voff)[_i]), (PG8_LAS unsigned*)(lds + (bufoff) + ldsw + _i * 8192), 16, 0, 0); } while (0)
; #define PG8_LDA(dst, b, h) do { _Pragma("unroll") for (int m = 0; m < 4; ++m) _Pragma("unroll") for (int k = 0; k < 2; ++k) dst[m][k] = *(const PG8_LAS bf16x8*)(lds + PG8_SA(b, h) + aoff + m * 2048 + k * 1024); } while (0)
; #define PG8_LDB(dst, b, h) do { _Pragma("unroll") for (int n = 0; n < 2; ++n) _Pragma("unroll") for (int k = 0; k < 2; ++k) dst[n][k] = *(const PG8_LAS bf16x8*)(lds + PG8_SB(b, h) + boff + n * 2048 + k * 1024); } while (0)
; #define PG8_MMA(ai, bj, At, Bt) do { __builtin_amdgcn_s_setprio(1); _Pragma("unroll") for (int m = 0; m < 4; ++m) _Pragma("unroll") for (int n = 0; n < 2; ++n) _Pragma("unroll") for (int k = 0; k < 2; ++k) \
;         acc[ai][bj][m][n] = __builtin_amdgcn_mfma_f32_16x16x32_bf16(Bt[n][k], At[m][k], acc[ai][bj][m][n], 0, 0, 0); __builtin_amdgcn_s_setprio(0); } while (0)
; #define PG8_WAIT_V(n) asm volatile("s_waitcnt vmcnt(" #n ")" ::: "memory")
; #define PG8_WAIT_L(n) asm volatile("s_waitcnt lgkmcnt(" #n ")" ::: "memory")
; #define PG8_BAR __builtin_amdgcn_s_barrier()
; #define PG8_SCHED __builtin_amdgcn_sched_barrier(0)
; template <class Epi, class Sched, bool ALIGN_EPI = false, bool SP2 = false>
; __device__ __forceinline__ void gemm_phase(PG8_LAS unsigned char* lds, const Gemm g, const Sched& S, const Epi& E) {
;     ...
;     f32x4 acc[2][2][4][2];
; #pragma unroll
;     for (int a = 0; a < 2; ++a)
; #pragma unroll
;         for (int b = 0; b < 2; ++b)
; #pragma unroll
;             for (int m = 0; m < 4; ++m)
; #pragma unroll
;                 for (int n = 0; n < 2; ++n) acc[a][b][m][n] = (f32x4){0.f, 0.f, 0.f, 0.f};
;     ...
;             PG8_LDB(B0, 0, 0); PG8_LDB(B1, 0, 1); PG8_SCHED; PG8_LDA(At, 0, 0); PG8_STAGE(PG8_SA(1, 1), a1 + hstep, voffA);
;             PG8_WAIT_V(8); PG8_WAIT_L(0); PG8_BAR; PG8_MMA(0, 0, At, B0); PG8_MMA(0, 1, At, B1); PG8_BAR; PG8_SCHED;
.LBB0_1208:
	s_add_u32 s66, s30, 0x100
	v_mov_b32_e32 v0, 0
	s_addc_u32 s67, s31, 0
	s_mov_b32 s68, -2
	v_mov_b32_e32 v1, v0
	v_mov_b32_e32 v2, v0
	v_mov_b32_e32 v3, v0
	v_mov_b32_e32 v4, v0
	v_mov_b32_e32 v5, v0
	v_mov_b32_e32 v6, v0
	v_mov_b32_e32 v7, v0
	v_mov_b32_e32 v8, v0
	v_mov_b32_e32 v9, v0
	v_mov_b32_e32 v10, v0
	v_mov_b32_e32 v11, v0
	v_mov_b32_e32 v12, v0
	v_mov_b32_e32 v13, v0
	v_mov_b32_e32 v14, v0
	v_mov_b32_e32 v15, v0
	v_mov_b32_e32 v16, v0
	v_mov_b32_e32 v17, v0
	v_mov_b32_e32 v18, v0
	v_mov_b32_e32 v19, v0
	v_mov_b32_e32 v20, v0
	v_mov_b32_e32 v21, v0
	v_mov_b32_e32 v22, v0
	v_mov_b32_e32 v23, v0
	v_mov_b32_e32 v24, v0
	v_mov_b32_e32 v25, v0
	v_mov_b32_e32 v26, v0
	v_mov_b32_e32 v27, v0
	v_mov_b32_e32 v28, v0
	v_mov_b32_e32 v29, v0
	v_mov_b32_e32 v30, v0
	v_mov_b32_e32 v31, v0
	v_mov_b32_e32 v48, v0
	v_mov_b32_e32 v49, v0
	v_mov_b32_e32 v50, v0
	v_mov_b32_e32 v51, v0
	v_mov_b32_e32 v56, v0
	v_mov_b32_e32 v57, v0
	v_mov_b32_e32 v58, v0
	v_mov_b32_e32 v59, v0
	v_mov_b32_e32 v64, v0
	v_mov_b32_e32 v65, v0
	v_mov_b32_e32 v66, v0
	v_mov_b32_e32 v67, v0
	v_mov_b32_e32 v72, v0
	v_mov_b32_e32 v73, v0
	v_mov_b32_e32 v74, v0
	v_mov_b32_e32 v75, v0
	v_mov_b32_e32 v80, v0
	v_mov_b32_e32 v81, v0
	v_mov_b32_e32 v82, v0
	v_mov_b32_e32 v83, v0
	v_mov_b32_e32 v84, v0
	v_mov_b32_e32 v85, v0
	v_mov_b32_e32 v86, v0
	v_mov_b32_e32 v87, v0
	v_mov_b32_e32 v88, v0
	v_mov_b32_e32 v89, v0
	v_mov_b32_e32 v90, v0
	v_mov_b32_e32 v91, v0
	v_mov_b32_e32 v92, v0
	v_mov_b32_e32 v93, v0
	v_mov_b32_e32 v94, v0
	v_mov_b32_e32 v95, v0
	v_mov_b32_e32 v32, v0
	v_mov_b32_e32 v33, v0
	v_mov_b32_e32 v34, v0
	v_mov_b32_e32 v35, v0
	v_mov_b32_e32 v36, v0
	v_mov_b32_e32 v37, v0
	v_mov_b32_e32 v38, v0
	v_mov_b32_e32 v39, v0
	v_mov_b32_e32 v40, v0
	v_mov_b32_e32 v41, v0
	v_mov_b32_e32 v42, v0
	v_mov_b32_e32 v43, v0
	v_mov_b32_e32 v44, v0
	v_mov_b32_e32 v45, v0
	v_mov_b32_e32 v46, v0
	v_mov_b32_e32 v47, v0
	v_mov_b32_e32 v52, v0
	v_mov_b32_e32 v53, v0
	v_mov_b32_e32 v54, v0
	v_mov_b32_e32 v55, v0
	v_mov_b32_e32 v60, v0
	v_mov_b32_e32 v61, v0
	v_mov_b32_e32 v62, v0
	v_mov_b32_e32 v63, v0
	v_mov_b32_e32 v68, v0
	v_mov_b32_e32 v69, v0
	v_mov_b32_e32 v70, v0
	v_mov_b32_e32 v71, v0
	v_mov_b32_e32 v76, v0
	v_mov_b32_e32 v77, v0
	v_mov_b32_e32 v78, v0
	v_mov_b32_e32 v79, v0
	v_mov_b32_e32 v96, v0
	v_mov_b32_e32 v97, v0
	v_mov_b32_e32 v98, v0
	v_mov_b32_e32 v99, v0
	v_mov_b32_e32 v100, v0
	v_mov_b32_e32 v101, v0
	v_mov_b32_e32 v102, v0
	v_mov_b32_e32 v103, v0
	v_mov_b32_e32 v104, v0
	v_mov_b32_e32 v105, v0
	v_mov_b32_e32 v106, v0
	v_mov_b32_e32 v107, v0
	v_mov_b32_e32 v108, v0
	v_mov_b32_e32 v109, v0
	v_mov_b32_e32 v110, v0
	v_mov_b32_e32 v111, v0
	v_mov_b32_e32 v112, v0
	v_mov_b32_e32 v113, v0
	v_mov_b32_e32 v114, v0
	v_mov_b32_e32 v115, v0
	v_mov_b32_e32 v116, v0
	v_mov_b32_e32 v117, v0
	v_mov_b32_e32 v118, v0
	v_mov_b32_e32 v119, v0
	v_mov_b32_e32 v120, v0
	v_mov_b32_e32 v121, v0
	v_mov_b32_e32 v122, v0
	v_mov_b32_e32 v123, v0
	v_mov_b32_e32 v124, v0
	v_mov_b32_e32 v125, v0
	v_mov_b32_e32 v126, v0
	v_mov_b32_e32 v127, v0
	ds_read_b128 v[150:153], v147
	ds_read_b128 v[154:157], v235
	ds_read_b128 v[158:161], v147 offset:2048
	ds_read_b128 v[162:165], v235 offset:2048
.LBB0_1209:
	ds_read_b128 v[166:169], v148
	ds_read_b128 v[170:173], v236
	ds_read_b128 v[174:177], v148 offset:2048
	ds_read_b128 v[178:181], v236 offset:2048
	s_add_u32 s30, s28, 0x100
	s_addc_u32 s31, s29, 0
	s_cmp_eq_u32 s68, 40
	s_cselect_b32 s37, s9, s31
	s_cselect_b32 s36, s8, s30
	s_cselect_b32 s35, s27, s67
	s_cselect_b32 s34, s26, s66
	v_lshl_add_u64 v[222:223], s[28:29], 0, v[136:137]
	s_add_i32 m0, s47, 0xc000
	ds_read_b128 v[190:193], v149
	ds_read_b128 v[194:197], v233
	ds_read_b128 v[198:201], v149 offset:2048
	ds_read_b128 v[202:205], v233 offset:2048
	ds_read_b128 v[206:209], v149 offset:4096
	ds_read_b128 v[210:213], v233 offset:4096
	ds_read_b128 v[214:217], v149 offset:6144
	ds_read_b128 v[218:221], v233 offset:6144
	global_load_lds_dwordx4 v[222:223], off
	v_lshl_add_u64 v[222:223], s[28:29], 0, v[138:139]
	s_add_i32 m0, s47, 0xe000
	s_nop 0
	global_load_lds_dwordx4 v[222:223], off
	s_waitcnt vmcnt(8)
	s_waitcnt lgkmcnt(0)
	s_barrier
	s_setprio 1
	s_waitcnt lgkmcnt(0)
	v_mfma_f32_16x16x32_bf16 v[124:127], v[150:153], v[190:193], v[124:127]
	v_mfma_f32_16x16x32_bf16 v[120:123], v[158:161], v[190:193], v[120:123]
	v_mfma_f32_16x16x32_bf16 v[116:119], v[150:153], v[198:201], v[116:119]
	v_mfma_f32_16x16x32_bf16 v[112:115], v[158:161], v[198:201], v[112:115]
	v_mfma_f32_16x16x32_bf16 v[108:111], v[150:153], v[206:209], v[108:111]
	v_mfma_f32_16x16x32_bf16 v[104:107], v[158:161], v[206:209], v[104:107]
	v_mfma_f32_16x16x32_bf16 v[100:103], v[150:153], v[214:217], v[100:103]
	v_mfma_f32_16x16x32_bf16 v[96:99], v[158:161], v[214:217], v[96:99]
	v_mfma_f32_16x16x32_bf16 v[124:127], v[154:157], v[194:197], v[124:127]
	v_mfma_f32_16x16x32_bf16 v[120:123], v[162:165], v[194:197], v[120:123]
	v_mfma_f32_16x16x32_bf16 v[116:119], v[154:157], v[202:205], v[116:119]
	v_mfma_f32_16x16x32_bf16 v[112:115], v[162:165], v[202:205], v[112:115]
	v_mfma_f32_16x16x32_bf16 v[108:111], v[154:157], v[210:213], v[108:111]
	v_mfma_f32_16x16x32_bf16 v[104:107], v[162:165], v[210:213], v[104:107]
	v_mfma_f32_16x16x32_bf16 v[100:103], v[154:157], v[218:221], v[100:103]
	v_mfma_f32_16x16x32_bf16 v[96:99], v[162:165], v[218:221], v[96:99]
	s_setprio 0
	s_setprio 1
	v_mfma_f32_16x16x32_bf16 v[76:79], v[166:169], v[190:193], v[76:79]
	v_mfma_f32_16x16x32_bf16 v[68:71], v[174:177], v[190:193], v[68:71]
	v_mfma_f32_16x16x32_bf16 v[60:63], v[166:169], v[198:201], v[60:63]
	v_mfma_f32_16x16x32_bf16 v[52:55], v[174:177], v[198:201], v[52:55]
	v_mfma_f32_16x16x32_bf16 v[44:47], v[166:169], v[206:209], v[44:47]
	v_mfma_f32_16x16x32_bf16 v[40:43], v[174:177], v[206:209], v[40:43]
	v_mfma_f32_16x16x32_bf16 v[36:39], v[166:169], v[214:217], v[36:39]
	v_mfma_f32_16x16x32_bf16 v[32:35], v[174:177], v[214:217], v[32:35]
	v_mfma_f32_16x16x32_bf16 v[76:79], v[170:173], v[194:197], v[76:79]
	v_mfma_f32_16x16x32_bf16 v[68:71], v[178:181], v[194:197], v[68:71]
	v_mfma_f32_16x16x32_bf16 v[60:63], v[170:173], v[202:205], v[60:63]
	v_mfma_f32_16x16x32_bf16 v[52:55], v[178:181], v[202:205], v[52:55]
	v_mfma_f32_16x16x32_bf16 v[44:47], v[170:173], v[210:213], v[44:47]
	v_mfma_f32_16x16x32_bf16 v[40:43], v[178:181], v[210:213], v[40:43]
	v_mfma_f32_16x16x32_bf16 v[36:39], v[170:173], v[218:221], v[36:39]
	v_mfma_f32_16x16x32_bf16 v[32:35], v[178:181], v[218:221], v[32:35]
	s_setprio 0
	s_barrier
; #define PG8_STAGE(bufoff, gbase, voff) do { _Pragma("unroll") for (int _i = 0; _i < 2; ++_i) \
;         __builtin_amdgcn_global_load_lds((const unsigned*)((const char*)(gbase) + (voff)[_i]), (PG8_LAS unsigned*)(lds + (bufoff) + ldsw + _i * 8192), 16, 0, 0); } while (0)
; #define PG8_LDA(dst, b, h) do { _Pragma("unroll") for (int m = 0; m < 4; ++m) _Pragma("unroll") for (int k = 0; k < 2; ++k) dst[m][k] = *(const PG8_LAS bf16x8*)(lds + PG8_SA(b, h) + aoff + m * 2048 + k * 1024); } while (0)
; #define PG8_LDB(dst, b, h) do { _Pragma("unroll") for (int n = 0; n < 2; ++n) _Pragma("unroll") for (int k = 0; k < 2; ++k) dst[n][k] = *(const PG8_LAS bf16x8*)(lds + PG8_SB(b, h) + boff + n * 2048 + k * 1024); } while (0)
; #define PG8_MMA(ai, bj, At, Bt) do { __builtin_amdgcn_s_setprio(1); _Pragma("unroll") for (int m = 0; m < 4; ++m) _Pragma("unroll") for (int n = 0; n < 2; ++n) _Pragma("unroll") for (int k = 0; k < 2; ++k) \
;         acc[ai][bj][m][n] = __builtin_amdgcn_mfma_f32_16x16x32_bf16(Bt[n][k], At[m][k], acc[ai][bj][m][n], 0, 0, 0); __builtin_amdgcn_s_setprio(0); } while (0)
; #define PG8_WAIT_V(n) asm volatile("s_waitcnt vmcnt(" #n ")" ::: "memory")
; #define PG8_WAIT_L(n) asm volatile("s_waitcnt lgkmcnt(" #n ")" ::: "memory")
; #define PG8_BAR __builtin_amdgcn_s_barrier()
; #define PG8_SCHED __builtin_amdgcn_sched_barrier(0)
; template <class Epi, class Sched, bool ALIGN_EPI = false, bool SP2 = false>
; __device__ __forceinline__ void gemm_phase(PG8_LAS unsigned char* lds, const Gemm g, const Sched& S, const Epi& E) {
;     ...
;             PG8_LDA(At, 0, 1); PG8_STAGE(PG8_SB(0, 0), b2, voffB); PG8_STAGE(PG8_SB(0, 1), b2 + hstep, voffB); PG8_STAGE(PG8_SA(0, 0), a2, voffA);
;             PG8_WAIT_V(8); PG8_WAIT_L(0); PG8_BAR; PG8_MMA(1, 0, At, B0); PG8_MMA(1, 1, At, B1); PG8_BAR; PG8_SCHED;
;             PG8_LDB(B0, 1, 0); PG8_LDB(B1, 1, 1); PG8_SCHED; PG8_LDA(At, 1, 0); PG8_STAGE(PG8_SA(0, 1), a2 + hstep, voffA);
;             PG8_WAIT_V(8); PG8_WAIT_L(0); PG8_BAR; PG8_MMA(0, 0, At, B0); PG8_MMA(0, 1, At, B1); PG8_BAR; PG8_SCHED;
	s_add_i32 s0, s56, s43
	v_lshl_add_u64 v[222:223], s[34:35], 0, v[130:131]
	s_mov_b32 m0, s0
	ds_read_b128 v[190:193], v149 offset:16384
	ds_read_b128 v[194:197], v233 offset:16384
	ds_read_b128 v[198:201], v149 offset:18432
	ds_read_b128 v[202:205], v233 offset:18432
	ds_read_b128 v[206:209], v149 offset:20480
	ds_read_b128 v[210:213], v233 offset:20480
	ds_read_b128 v[214:217], v149 offset:22528
	ds_read_b128 v[218:221], v233 offset:22528
	global_load_lds_dwordx4 v[222:223], off
	s_add_i32 m0, s0, 0x2000
	s_add_u32 s0, s34, 0xb0000
	v_lshl_add_u64 v[224:225], s[34:35], 0, v[134:135]
	s_addc_u32 s1, s35, 0
	s_add_i32 s3, s57, s43
	global_load_lds_dwordx4 v[224:225], off
	v_lshl_add_u64 v[226:227], s[0:1], 0, v[130:131]
	s_mov_b32 m0, s3
	v_lshl_add_u64 v[228:229], s[36:37], 0, v[132:133]
	global_load_lds_dwordx4 v[226:227], off
	v_lshl_add_u64 v[226:227], s[0:1], 0, v[134:135]
	s_add_i32 m0, s3, 0x2000
	s_nop 0
	global_load_lds_dwordx4 v[226:227], off
	v_lshl_add_u64 v[226:227], s[36:37], 0, v[128:129]
	s_mov_b32 m0, s47
	s_nop 0
	global_load_lds_dwordx4 v[226:227], off
	s_mov_b32 m0, s48
	s_nop 0
	global_load_lds_dwordx4 v[228:229], off
	s_waitcnt vmcnt(8)
	s_waitcnt lgkmcnt(0)
	s_barrier
	s_setprio 1
	s_waitcnt lgkmcnt(0)
	ds_read_b128 v[240:243], v239
	ds_read_b128 v[244:247], v237
	ds_read_b128 v[248:251], v239 offset:2048
	ds_read_b128 v[252:255], v237 offset:2048
	v_mfma_f32_16x16x32_bf16 v[92:95], v[150:153], v[190:193], v[92:95]
	v_mfma_f32_16x16x32_bf16 v[88:91], v[158:161], v[190:193], v[88:91]
	v_mfma_f32_16x16x32_bf16 v[84:87], v[150:153], v[198:201], v[84:87]
	v_mfma_f32_16x16x32_bf16 v[80:83], v[158:161], v[198:201], v[80:83]
	v_mfma_f32_16x16x32_bf16 v[72:75], v[150:153], v[206:209], v[72:75]
	v_mfma_f32_16x16x32_bf16 v[64:67], v[158:161], v[206:209], v[64:67]
	v_mfma_f32_16x16x32_bf16 v[56:59], v[150:153], v[214:217], v[56:59]
	v_mfma_f32_16x16x32_bf16 v[48:51], v[158:161], v[214:217], v[48:51]
	v_mfma_f32_16x16x32_bf16 v[92:95], v[154:157], v[194:197], v[92:95]
	v_mfma_f32_16x16x32_bf16 v[88:91], v[162:165], v[194:197], v[88:91]
	v_mfma_f32_16x16x32_bf16 v[84:87], v[154:157], v[202:205], v[84:87]
	v_mfma_f32_16x16x32_bf16 v[80:83], v[162:165], v[202:205], v[80:83]
	v_mfma_f32_16x16x32_bf16 v[72:75], v[154:157], v[210:213], v[72:75]
	v_mfma_f32_16x16x32_bf16 v[64:67], v[162:165], v[210:213], v[64:67]
	v_mfma_f32_16x16x32_bf16 v[56:59], v[154:157], v[218:221], v[56:59]
	v_mfma_f32_16x16x32_bf16 v[48:51], v[162:165], v[218:221], v[48:51]
	s_setprio 0
	s_setprio 1
	v_mfma_f32_16x16x32_bf16 v[28:31], v[166:169], v[190:193], v[28:31]
	v_mfma_f32_16x16x32_bf16 v[24:27], v[174:177], v[190:193], v[24:27]
	v_mfma_f32_16x16x32_bf16 v[20:23], v[166:169], v[198:201], v[20:23]
	v_mfma_f32_16x16x32_bf16 v[16:19], v[174:177], v[198:201], v[16:19]
	v_mfma_f32_16x16x32_bf16 v[12:15], v[166:169], v[206:209], v[12:15]
	v_mfma_f32_16x16x32_bf16 v[8:11], v[174:177], v[206:209], v[8:11]
	v_mfma_f32_16x16x32_bf16 v[4:7], v[166:169], v[214:217], v[4:7]
	v_mfma_f32_16x16x32_bf16 v[0:3], v[174:177], v[214:217], v[0:3]
	v_mfma_f32_16x16x32_bf16 v[28:31], v[170:173], v[194:197], v[28:31]
	v_mfma_f32_16x16x32_bf16 v[24:27], v[178:181], v[194:197], v[24:27]
	v_mfma_f32_16x16x32_bf16 v[20:23], v[170:173], v[202:205], v[20:23]
	v_mfma_f32_16x16x32_bf16 v[16:19], v[178:181], v[202:205], v[16:19]
	v_mfma_f32_16x16x32_bf16 v[12:15], v[170:173], v[210:213], v[12:15]
	v_mfma_f32_16x16x32_bf16 v[8:11], v[178:181], v[210:213], v[8:11]
	v_mfma_f32_16x16x32_bf16 v[4:7], v[170:173], v[218:221], v[4:7]
	v_mfma_f32_16x16x32_bf16 v[0:3], v[178:181], v[218:221], v[0:3]
	s_setprio 0
	s_barrier
	s_add_i32 s3, 0, 0x18000
	s_add_i32 s28, 0, 0x1c000
	v_add_u32_e32 v178, s28, v145
	v_add_u32_e32 v238, s28, v234
	ds_read_b128 v[166:169], v178
	ds_read_b128 v[170:173], v238
	ds_read_b128 v[174:177], v178 offset:2048
	ds_read_b128 v[178:181], v238 offset:2048
	s_add_u32 s0, s36, 0xb0000
	s_addc_u32 s1, s37, 0
	s_mov_b32 m0, s49
	v_lshl_add_u64 v[230:231], s[0:1], 0, v[128:129]
	ds_read_b128 v[190:193], v149 offset:32768
	ds_read_b128 v[194:197], v233 offset:32768
	ds_read_b128 v[198:201], v149 offset:34816
	ds_read_b128 v[202:205], v233 offset:34816
	ds_read_b128 v[206:209], v149 offset:36864
	ds_read_b128 v[210:213], v233 offset:36864
	ds_read_b128 v[214:217], v149 offset:38912
	ds_read_b128 v[218:221], v233 offset:38912
	global_load_lds_dwordx4 v[230:231], off
	v_lshl_add_u64 v[230:231], s[0:1], 0, v[132:133]
	s_mov_b32 m0, s50
	s_nop 0
	global_load_lds_dwordx4 v[230:231], off
	s_waitcnt vmcnt(8)
	s_waitcnt lgkmcnt(0)
	s_barrier
; #define PG8_STAGE(bufoff, gbase, voff) do { _Pragma("unroll") for (int _i = 0; _i < 2; ++_i) \
;         __builtin_amdgcn_global_load_lds((const unsigned*)((const char*)(gbase) + (voff)[_i]), (PG8_LAS unsigned*)(lds + (bufoff) + ldsw + _i * 8192), 16, 0, 0); } while (0)
; #define PG8_LDA(dst, b, h) do { _Pragma("unroll") for (int m = 0; m < 4; ++m) _Pragma("unroll") for (int k = 0; k < 2; ++k) dst[m][k] = *(const PG8_LAS bf16x8*)(lds + PG8_SA(b, h) + aoff + m * 2048 + k * 1024); } while (0)
; #define PG8_LDB(dst, b, h) do { _Pragma("unroll") for (int n = 0; n < 2; ++n) _Pragma("unroll") for (int k = 0; k < 2; ++k) dst[n][k] = *(const PG8_LAS bf16x8*)(lds + PG8_SB(b, h) + boff + n * 2048 + k * 1024); } while (0)
; #define PG8_MMA(ai, bj, At, Bt) do { __builtin_amdgcn_s_setprio(1); _Pragma("unroll") for (int m = 0; m < 4; ++m) _Pragma("unroll") for (int n = 0; n < 2; ++n) _Pragma("unroll") for (int k = 0; k < 2; ++k) \
;         acc[ai][bj][m][n] = __builtin_amdgcn_mfma_f32_16x16x32_bf16(Bt[n][k], At[m][k], acc[ai][bj][m][n], 0, 0, 0); __builtin_amdgcn_s_setprio(0); } while (0)
; #define PG8_WAIT_V(n) asm volatile("s_waitcnt vmcnt(" #n ")" ::: "memory")
; #define PG8_WAIT_L(n) asm volatile("s_waitcnt lgkmcnt(" #n ")" ::: "memory")
; #define PG8_BAR __builtin_amdgcn_s_barrier()
; #define PG8_SCHED __builtin_amdgcn_sched_barrier(0)
; template <class Epi, class Sched, bool ALIGN_EPI = false, bool SP2 = false>
; __device__ __forceinline__ void gemm_phase(PG8_LAS unsigned char* lds, const Gemm g, const Sched& S, const Epi& E) {
;     ...
;             PG8_LDB(B0, 1, 0); PG8_LDB(B1, 1, 1); PG8_SCHED; PG8_LDA(At, 1, 0); PG8_STAGE(PG8_SA(0, 1), a2 + hstep, voffA);
;             PG8_WAIT_V(8); PG8_WAIT_L(0); PG8_BAR; PG8_MMA(0, 0, At, B0); PG8_MMA(0, 1, At, B1); PG8_BAR; PG8_SCHED;
;             PG8_LDA(At, 1, 1); PG8_STAGE(PG8_SB(1, 0), b3, voffB); PG8_STAGE(PG8_SB(1, 1), b3 + hstep, voffB); PG8_STAGE(PG8_SA(1, 0), a3, voffA);
;             PG8_WAIT_V(8); PG8_WAIT_L(0); PG8_BAR; PG8_MMA(1, 0, At, B0); PG8_MMA(1, 1, At, B1); PG8_BAR; PG8_SCHED;
	s_setprio 1
	s_waitcnt lgkmcnt(0)
	v_mfma_f32_16x16x32_bf16 v[124:127], v[240:243], v[190:193], v[124:127]
	v_mfma_f32_16x16x32_bf16 v[120:123], v[248:251], v[190:193], v[120:123]
	v_mfma_f32_16x16x32_bf16 v[116:119], v[240:243], v[198:201], v[116:119]
	v_mfma_f32_16x16x32_bf16 v[112:115], v[248:251], v[198:201], v[112:115]
	v_mfma_f32_16x16x32_bf16 v[108:111], v[240:243], v[206:209], v[108:111]
	v_mfma_f32_16x16x32_bf16 v[104:107], v[248:251], v[206:209], v[104:107]
	v_mfma_f32_16x16x32_bf16 v[100:103], v[240:243], v[214:217], v[100:103]
	v_mfma_f32_16x16x32_bf16 v[96:99], v[248:251], v[214:217], v[96:99]
	v_mfma_f32_16x16x32_bf16 v[124:127], v[244:247], v[194:197], v[124:127]
	v_mfma_f32_16x16x32_bf16 v[120:123], v[252:255], v[194:197], v[120:123]
	v_mfma_f32_16x16x32_bf16 v[116:119], v[244:247], v[202:205], v[116:119]
	v_mfma_f32_16x16x32_bf16 v[112:115], v[252:255], v[202:205], v[112:115]
	v_mfma_f32_16x16x32_bf16 v[108:111], v[244:247], v[210:213], v[108:111]
	v_mfma_f32_16x16x32_bf16 v[104:107], v[252:255], v[210:213], v[104:107]
	v_mfma_f32_16x16x32_bf16 v[100:103], v[244:247], v[218:221], v[100:103]
	v_mfma_f32_16x16x32_bf16 v[96:99], v[252:255], v[218:221], v[96:99]
	s_setprio 0
	s_setprio 1
	v_mfma_f32_16x16x32_bf16 v[76:79], v[166:169], v[190:193], v[76:79]
	v_mfma_f32_16x16x32_bf16 v[68:71], v[174:177], v[190:193], v[68:71]
	v_mfma_f32_16x16x32_bf16 v[60:63], v[166:169], v[198:201], v[60:63]
	v_mfma_f32_16x16x32_bf16 v[52:55], v[174:177], v[198:201], v[52:55]
	v_mfma_f32_16x16x32_bf16 v[44:47], v[166:169], v[206:209], v[44:47]
	v_mfma_f32_16x16x32_bf16 v[40:43], v[174:177], v[206:209], v[40:43]
	v_mfma_f32_16x16x32_bf16 v[36:39], v[166:169], v[214:217], v[36:39]
	v_mfma_f32_16x16x32_bf16 v[32:35], v[174:177], v[214:217], v[32:35]
	v_mfma_f32_16x16x32_bf16 v[76:79], v[170:173], v[194:197], v[76:79]
	v_mfma_f32_16x16x32_bf16 v[68:71], v[178:181], v[194:197], v[68:71]
	v_mfma_f32_16x16x32_bf16 v[60:63], v[170:173], v[202:205], v[60:63]
	v_mfma_f32_16x16x32_bf16 v[52:55], v[178:181], v[202:205], v[52:55]
	v_mfma_f32_16x16x32_bf16 v[44:47], v[170:173], v[210:213], v[44:47]
	v_mfma_f32_16x16x32_bf16 v[40:43], v[178:181], v[210:213], v[40:43]
	v_mfma_f32_16x16x32_bf16 v[36:39], v[170:173], v[218:221], v[36:39]
	v_mfma_f32_16x16x32_bf16 v[32:35], v[178:181], v[218:221], v[32:35]
	s_setprio 0
	s_barrier
	s_add_i32 s0, s3, s43
	v_lshl_add_u64 v[222:223], v[222:223], 0, s[14:15]
	s_mov_b32 m0, s0
	ds_read_b128 v[190:193], v149 offset:49152
	ds_read_b128 v[194:197], v233 offset:49152
	ds_read_b128 v[198:201], v149 offset:51200
	ds_read_b128 v[202:205], v233 offset:51200
	ds_read_b128 v[206:209], v149 offset:53248
	ds_read_b128 v[210:213], v233 offset:53248
	ds_read_b128 v[214:217], v149 offset:55296
	ds_read_b128 v[218:221], v233 offset:55296
	global_load_lds_dwordx4 v[222:223], off
	s_add_i32 m0, s0, 0x2000
	s_add_u32 s0, s34, 0xb0080
	v_lshl_add_u64 v[222:223], v[224:225], 0, s[14:15]
	s_addc_u32 s1, s35, 0
	s_add_i32 s3, s28, s43
	global_load_lds_dwordx4 v[222:223], off
	v_lshl_add_u64 v[222:223], s[0:1], 0, v[130:131]
	s_mov_b32 m0, s3
	s_nop 0
	global_load_lds_dwordx4 v[222:223], off
	v_lshl_add_u64 v[222:223], s[0:1], 0, v[134:135]
	s_add_i32 m0, s3, 0x2000
	s_nop 0
	global_load_lds_dwordx4 v[222:223], off
	v_lshl_add_u64 v[222:223], v[226:227], 0, s[14:15]
	s_mov_b32 m0, s52
	s_nop 0
	global_load_lds_dwordx4 v[222:223], off
	v_lshl_add_u64 v[222:223], v[228:229], 0, s[14:15]
	s_mov_b32 m0, s53
	s_nop 0
	global_load_lds_dwordx4 v[222:223], off
	s_waitcnt vmcnt(8)
	s_waitcnt lgkmcnt(0)
	s_barrier
	s_setprio 1
	s_waitcnt lgkmcnt(0)
	ds_read_b128 v[150:153], v147
	ds_read_b128 v[154:157], v235
	ds_read_b128 v[158:161], v147 offset:2048
	ds_read_b128 v[162:165], v235 offset:2048
	v_mfma_f32_16x16x32_bf16 v[92:95], v[240:243], v[190:193], v[92:95]
	v_mfma_f32_16x16x32_bf16 v[88:91], v[248:251], v[190:193], v[88:91]
	v_mfma_f32_16x16x32_bf16 v[84:87], v[240:243], v[198:201], v[84:87]
	v_mfma_f32_16x16x32_bf16 v[80:83], v[248:251], v[198:201], v[80:83]
	v_mfma_f32_16x16x32_bf16 v[72:75], v[240:243], v[206:209], v[72:75]
	v_mfma_f32_16x16x32_bf16 v[64:67], v[248:251], v[206:209], v[64:67]
	v_mfma_f32_16x16x32_bf16 v[56:59], v[240:243], v[214:217], v[56:59]
	v_mfma_f32_16x16x32_bf16 v[48:51], v[248:251], v[214:217], v[48:51]
	v_mfma_f32_16x16x32_bf16 v[92:95], v[244:247], v[194:197], v[92:95]
	v_mfma_f32_16x16x32_bf16 v[88:91], v[252:255], v[194:197], v[88:91]
	v_mfma_f32_16x16x32_bf16 v[84:87], v[244:247], v[202:205], v[84:87]
	v_mfma_f32_16x16x32_bf16 v[80:83], v[252:255], v[202:205], v[80:83]
	v_mfma_f32_16x16x32_bf16 v[72:75], v[244:247], v[210:213], v[72:75]
	v_mfma_f32_16x16x32_bf16 v[64:67], v[252:255], v[210:213], v[64:67]
	v_mfma_f32_16x16x32_bf16 v[56:59], v[244:247], v[218:221], v[56:59]
	v_mfma_f32_16x16x32_bf16 v[48:51], v[252:255], v[218:221], v[48:51]
	s_setprio 0
	s_setprio 1
	v_mfma_f32_16x16x32_bf16 v[28:31], v[166:169], v[190:193], v[28:31]
	v_mfma_f32_16x16x32_bf16 v[24:27], v[174:177], v[190:193], v[24:27]
	v_mfma_f32_16x16x32_bf16 v[20:23], v[166:169], v[198:201], v[20:23]
	v_mfma_f32_16x16x32_bf16 v[16:19], v[174:177], v[198:201], v[16:19]
	v_mfma_f32_16x16x32_bf16 v[12:15], v[166:169], v[206:209], v[12:15]
	v_mfma_f32_16x16x32_bf16 v[8:11], v[174:177], v[206:209], v[8:11]
	v_mfma_f32_16x16x32_bf16 v[4:7], v[166:169], v[214:217], v[4:7]
	v_mfma_f32_16x16x32_bf16 v[0:3], v[174:177], v[214:217], v[0:3]
	v_mfma_f32_16x16x32_bf16 v[28:31], v[170:173], v[194:197], v[28:31]
	v_mfma_f32_16x16x32_bf16 v[24:27], v[178:181], v[194:197], v[24:27]
	v_mfma_f32_16x16x32_bf16 v[20:23], v[170:173], v[202:205], v[20:23]
	v_mfma_f32_16x16x32_bf16 v[16:19], v[178:181], v[202:205], v[16:19]
	v_mfma_f32_16x16x32_bf16 v[12:15], v[170:173], v[210:213], v[12:15]
	v_mfma_f32_16x16x32_bf16 v[8:11], v[178:181], v[210:213], v[8:11]
	v_mfma_f32_16x16x32_bf16 v[4:7], v[170:173], v[218:221], v[4:7]
	v_mfma_f32_16x16x32_bf16 v[0:3], v[178:181], v[218:221], v[0:3]
	s_setprio 0
	s_barrier
	s_add_i32 s68, s68, 2
	s_add_u32 s66, s66, 0x100
	s_addc_u32 s67, s67, 0
	s_cmp_gt_u32 s68, 41
	s_mov_b64 s[28:29], s[30:31]
	s_cbranch_scc0 .LBB0_1209
	s_waitcnt lgkmcnt(0)
	s_and_b64 vcc, exec, s[16:17]
	s_cbranch_vccz .LBB0_1212
	s_barrier
